# v51 + FFN1 epilogue U stores use sc1 write-through only on each workgroup's last unit of the phase (less dirty L2 at the grid barrier)
# speedup vs baseline: 1.0048x; 1.0048x over previous
; __device__ __forceinline__ unsigned cvt_pk_bf16(float lo, float hi) { unsigned r; asm volatile("v_cvt_pk_bf16_f32 %0, %1, %2" : "=v"(r) : "v"(lo), "v"(hi)); return r; }
; __device__ __forceinline__ float silu_f(float a) { return a * __builtin_amdgcn_rcpf(1.0f + __expf(-a)); }
;     __device__ __forceinline__ void operator()(const f32x4 (&acc)[2][2][4][2], const pg8::Unit& u, int wr, int wc, int fr, int fq) const {
;     ...
;                         u32x2 w; w.x = cvt_pk_bf16(silu_f(pre[m][0]) * vv[0], silu_f(pre[m][1]) * vv[1]); w.y = cvt_pk_bf16(silu_f(pre[m][2]) * vv[2], silu_f(pre[m][3]) * vv[3]);
;                         if (n == 0) uw0[m] = w;
;                         else if (!need_fix) { const int row = rowt + lane_r + ai * 128 + m * 16; *(u32x4*)(U + (size_t)row * DFF + fb) = (u32x4){uw0[m].x, uw0[m].y, w.x, w.y}; }
.Lmy_f1_u00:
	s_cmp_lg_u64 s[38:39], 0
	s_cbranch_scc0 .Lmy_f1_ns0
	global_store_dwordx4 v204, v[122:125], s[0:1] sc1
	s_branch .Lmy_f1_ds0

; __device__ __forceinline__ unsigned cvt_pk_bf16(float lo, float hi) { unsigned r; asm volatile("v_cvt_pk_bf16_f32 %0, %1, %2" : "=v"(r) : "v"(lo), "v"(hi)); return r; }
; __device__ __forceinline__ float silu_f(float a) { return a * __builtin_amdgcn_rcpf(1.0f + __expf(-a)); }
;     __device__ __forceinline__ void operator()(const f32x4 (&acc)[2][2][4][2], const pg8::Unit& u, int wr, int wc, int fr, int fq) const {
;     ...
;                     for (int m = 0; m < 4; ++m) {
;                         const bool top = (m == 0 && fr == 0), bot = (m == 3 && fr == 15);
;                         const bool need_fix = (top && !seq_first) || (bot && !seq_last);
;                         const f32x4 vv = acc[ai][1][m][n];
;                         if (top || bot) {
;                             float* e = EDGE + ((size_t)(chunk * 2 + (bot ? 1 : 0)) * 3) * DFF + f0;
;                             *(f32x4*)e = acc[ai][0][m][n];
;                             if (need_fix) { *(f32x4*)(e + DFF) = pre[m]; *(f32x4*)(e + 2 * DFF) = vv; }
;                         }
;                         u32x2 w; w.x = cvt_pk_bf16(silu_f(pre[m][0]) * vv[0], silu_f(pre[m][1]) * vv[1]); w.y = cvt_pk_bf16(silu_f(pre[m][2]) * vv[2], silu_f(pre[m][3]) * vv[3]);
;                         if (n == 0) uw0[m] = w;
;                         else if (!need_fix) { const int row = rowt + lane_r + ai * 128 + m * 16; *(u32x4*)(U + (size_t)row * DFF + fb) = (u32x4){uw0[m].x, uw0[m].y, w.x, w.y}; }
.Lmy_f1_ds0:
	s_mov_b64 exec, s[56:57]
	s_add_u32 s0, s44, 0x16000
	s_addc_u32 s1, s45, 0
	s_cmp_lg_u64 s[38:39], 0
	s_cbranch_scc0 .Lmy_f1_ns1
	global_store_dwordx4 v204, v[106:109], s[0:1] sc1
	s_branch .Lmy_f1_ds1
.Lmy_f1_ns1:
	global_store_dwordx4 v204, v[106:109], s[0:1]
.Lmy_f1_ds1:
	s_add_u32 s0, s44, 0x2c000
	s_addc_u32 s1, s45, 0
	s_cmp_lg_u64 s[38:39], 0
	s_cbranch_scc0 .Lmy_f1_ns2
	global_store_dwordx4 v204, v[90:93], s[0:1] sc1
	s_branch .Lmy_f1_ds2
.Lmy_f1_ns2:
	global_store_dwordx4 v204, v[90:93], s[0:1]
.Lmy_f1_ds2:
	s_add_u32 s0, s44, 0x42000
	s_addc_u32 s1, s45, 0
	s_bitcmp1_b32 s27, 1
	s_cbranch_scc0 .Lmy_f1_u03
	s_andn2_b64 exec, s[56:57], s[40:41]
.Lmy_f1_u03:
	s_cmp_lg_u64 s[38:39], 0
	s_cbranch_scc0 .Lmy_f1_ns3
	global_store_dwordx4 v204, v[82:85], s[0:1] sc1
	s_branch .Lmy_f1_ds3

;     __device__ __forceinline__ void operator()(const f32x4 (&acc)[2][2][4][2], const pg8::Unit& u, int wr, int wc, int fr, int fq) const {
;     ...
;             for (int ai = 0; ai < 2; ++ai) {
;                 const int chunk = u.pm * 4 + ai * 2 + wr;
;                 const int cseq = lat ? (chunk & 63) : ((chunk - MLAT / 64) & 3);
;                 const bool seq_first = cseq == 0, seq_last = lat ? (cseq == 63) : (cseq == 3);
;                 const int fb = u.pn * 128 + wc * 32 + 8 * fq;
;                 u32x2 uw0[4];
; #pragma unroll
;                 for (int n = 0; n < 2; ++n) {
;                     const int f0 = fb + 4 * n;
;                     const f32x4 w0 = *(const f32x4*)(cw + f0), w1 = *(const f32x4*)(cw + DFF + f0), w2 = *(const f32x4*)(cw + 2 * DFF + f0), bb = *(const f32x4*)(cb + f0);
;                     f32x4 pre[4];
; #pragma unroll
;                     for (int j = 0; j < 4; ++j) {
;                         float t[4], up[4], dn[4];
; #pragma unroll
;                         for (int m = 0; m < 4; ++m) { t[m] = acc[ai][0][m][n][j];
;                             up[m] = __builtin_bit_cast(float, __builtin_amdgcn_update_dpp(0, __builtin_bit_cast(int, t[m]), 0x121, 0xf, 0xf, false));
;                             dn[m] = __builtin_bit_cast(float, __builtin_amdgcn_update_dpp(0, __builtin_bit_cast(int, t[m]), 0x12F, 0xf, 0xf, false)); }
; #pragma unroll
;                         for (int m = 0; m < 4; ++m) {
;                             const float pv = (fr == 0) ? (m > 0 ? up[m > 0 ? m - 1 : 0] : 0.f) : up[m];
;                             const float nx = (fr == 15) ? (m < 3 ? dn[m < 3 ? m + 1 : 3] : 0.f) : dn[m];
;                             pre[m][j] = w0[j] * pv + w1[j] * t[m] + w2[j] * nx + bb[j];
;                         }
;                     }
; #pragma unroll
;                     for (int m = 0; m < 4; ++m) {
;                         const bool top = (m == 0 && fr == 0), bot = (m == 3 && fr == 15);
;                         const bool need_fix = (top && !seq_first) || (bot && !seq_last);
;                         const f32x4 vv = acc[ai][1][m][n];
;                         if (top || bot) {
;                             float* e = EDGE + ((size_t)(chunk * 2 + (bot ? 1 : 0)) * 3) * DFF + f0;
;                             *(f32x4*)e = acc[ai][0][m][n];
.Lmy_f1_ds3:
	s_mov_b64 exec, s[56:57]
	s_add_i32 s1, s51, 2
	s_and_b32 s0, s1, s25
	s_cmp_lg_u32 s0, 0
	s_cselect_b32 s27, 1, 0
	s_cmp_lg_u32 s0, s25
	s_cselect_b32 s0, 2, 0
	s_or_b32 s27, s27, s0
	s_lshl_b32 s1, s1, 1
	s_mul_i32 s1, s1, 0x8400
	s_add_u32 s30, s66, s1
	s_addc_u32 s31, s67, 0
	v_pk_fma_f32 v[166:167], v[146:147], v[74:75], v[154:155]
	v_pk_fma_f32 v[168:169], v[148:149], v[76:77], v[156:157]
	v_pk_fma_f32 v[170:171], v[146:147], v[66:67], v[154:155]
	v_pk_fma_f32 v[172:173], v[148:149], v[68:69], v[156:157]
	v_pk_fma_f32 v[174:175], v[146:147], v[50:51], v[154:155]
	v_pk_fma_f32 v[176:177], v[148:149], v[52:53], v[156:157]
	v_pk_fma_f32 v[178:179], v[146:147], v[34:35], v[154:155]
	v_pk_fma_f32 v[180:181], v[148:149], v[36:37], v[156:157]
	v_fmac_f32_dpp v166, v74, v142 row_shr:1 row_mask:0xf bank_mask:0xf bound_ctrl:0
	v_fmac_f32_dpp v167, v75, v143 row_shr:1 row_mask:0xf bank_mask:0xf bound_ctrl:0
	v_fmac_f32_dpp v168, v76, v144 row_shr:1 row_mask:0xf bank_mask:0xf bound_ctrl:0
	v_fmac_f32_dpp v169, v77, v145 row_shr:1 row_mask:0xf bank_mask:0xf bound_ctrl:0
	v_fmac_f32_dpp v170, v66, v142 row_shr:1 row_mask:0xf bank_mask:0xf bound_ctrl:0
	v_fmac_f32_dpp v171, v67, v143 row_shr:1 row_mask:0xf bank_mask:0xf bound_ctrl:0
	v_fmac_f32_dpp v172, v68, v144 row_shr:1 row_mask:0xf bank_mask:0xf bound_ctrl:0
	v_fmac_f32_dpp v173, v69, v145 row_shr:1 row_mask:0xf bank_mask:0xf bound_ctrl:0
	v_fmac_f32_dpp v174, v50, v142 row_shr:1 row_mask:0xf bank_mask:0xf bound_ctrl:0
	v_fmac_f32_dpp v175, v51, v143 row_shr:1 row_mask:0xf bank_mask:0xf bound_ctrl:0
	v_fmac_f32_dpp v176, v52, v144 row_shr:1 row_mask:0xf bank_mask:0xf bound_ctrl:0
	v_fmac_f32_dpp v177, v53, v145 row_shr:1 row_mask:0xf bank_mask:0xf bound_ctrl:0
	v_fmac_f32_dpp v178, v34, v142 row_shr:1 row_mask:0xf bank_mask:0xf bound_ctrl:0
	v_fmac_f32_dpp v179, v35, v143 row_shr:1 row_mask:0xf bank_mask:0xf bound_ctrl:0
	v_fmac_f32_dpp v180, v36, v144 row_shr:1 row_mask:0xf bank_mask:0xf bound_ctrl:0
	v_fmac_f32_dpp v181, v37, v145 row_shr:1 row_mask:0xf bank_mask:0xf bound_ctrl:0
	v_fmac_f32_dpp v170, v74, v158 row_ror:1 row_mask:0xf bank_mask:0xf
	v_fmac_f32_dpp v171, v75, v159 row_ror:1 row_mask:0xf bank_mask:0xf
	v_fmac_f32_dpp v172, v76, v160 row_ror:1 row_mask:0xf bank_mask:0xf
	v_fmac_f32_dpp v173, v77, v161 row_ror:1 row_mask:0xf bank_mask:0xf
	v_fmac_f32_dpp v174, v66, v158 row_ror:1 row_mask:0xf bank_mask:0xf
	v_fmac_f32_dpp v175, v67, v159 row_ror:1 row_mask:0xf bank_mask:0xf
	v_fmac_f32_dpp v176, v68, v160 row_ror:1 row_mask:0xf bank_mask:0xf
	v_fmac_f32_dpp v177, v69, v161 row_ror:1 row_mask:0xf bank_mask:0xf
	v_fmac_f32_dpp v178, v50, v158 row_ror:1 row_mask:0xf bank_mask:0xf
	v_fmac_f32_dpp v179, v51, v159 row_ror:1 row_mask:0xf bank_mask:0xf
	v_fmac_f32_dpp v180, v52, v160 row_ror:1 row_mask:0xf bank_mask:0xf
	v_fmac_f32_dpp v181, v53, v161 row_ror:1 row_mask:0xf bank_mask:0xf
	v_fmac_f32_dpp v166, v74, v150 row_shl:1 row_mask:0xf bank_mask:0xf bound_ctrl:0
	v_fmac_f32_dpp v167, v75, v151 row_shl:1 row_mask:0xf bank_mask:0xf bound_ctrl:0
	v_fmac_f32_dpp v168, v76, v152 row_shl:1 row_mask:0xf bank_mask:0xf bound_ctrl:0
	v_fmac_f32_dpp v169, v77, v153 row_shl:1 row_mask:0xf bank_mask:0xf bound_ctrl:0
	v_fmac_f32_dpp v170, v66, v150 row_shl:1 row_mask:0xf bank_mask:0xf bound_ctrl:0
	v_fmac_f32_dpp v171, v67, v151 row_shl:1 row_mask:0xf bank_mask:0xf bound_ctrl:0
	v_fmac_f32_dpp v172, v68, v152 row_shl:1 row_mask:0xf bank_mask:0xf bound_ctrl:0
	v_fmac_f32_dpp v173, v69, v153 row_shl:1 row_mask:0xf bank_mask:0xf bound_ctrl:0
	v_fmac_f32_dpp v174, v50, v150 row_shl:1 row_mask:0xf bank_mask:0xf bound_ctrl:0
	v_fmac_f32_dpp v175, v51, v151 row_shl:1 row_mask:0xf bank_mask:0xf bound_ctrl:0
	v_fmac_f32_dpp v176, v52, v152 row_shl:1 row_mask:0xf bank_mask:0xf bound_ctrl:0
	v_fmac_f32_dpp v177, v53, v153 row_shl:1 row_mask:0xf bank_mask:0xf bound_ctrl:0
	v_fmac_f32_dpp v178, v34, v150 row_shl:1 row_mask:0xf bank_mask:0xf bound_ctrl:0
	v_fmac_f32_dpp v179, v35, v151 row_shl:1 row_mask:0xf bank_mask:0xf bound_ctrl:0
	v_fmac_f32_dpp v180, v36, v152 row_shl:1 row_mask:0xf bank_mask:0xf bound_ctrl:0
	v_fmac_f32_dpp v181, v37, v153 row_shl:1 row_mask:0xf bank_mask:0xf bound_ctrl:0
	v_fmac_f32_dpp v166, v66, v162 row_ror:15 row_mask:0xf bank_mask:0xf
	v_fmac_f32_dpp v167, v67, v163 row_ror:15 row_mask:0xf bank_mask:0xf
	v_fmac_f32_dpp v168, v68, v164 row_ror:15 row_mask:0xf bank_mask:0xf
	v_fmac_f32_dpp v169, v69, v165 row_ror:15 row_mask:0xf bank_mask:0xf
	v_fmac_f32_dpp v170, v50, v162 row_ror:15 row_mask:0xf bank_mask:0xf
	v_fmac_f32_dpp v171, v51, v163 row_ror:15 row_mask:0xf bank_mask:0xf
	v_fmac_f32_dpp v172, v52, v164 row_ror:15 row_mask:0xf bank_mask:0xf
	v_fmac_f32_dpp v173, v53, v165 row_ror:15 row_mask:0xf bank_mask:0xf
	v_fmac_f32_dpp v174, v34, v162 row_ror:15 row_mask:0xf bank_mask:0xf
	v_fmac_f32_dpp v175, v35, v163 row_ror:15 row_mask:0xf bank_mask:0xf
	v_fmac_f32_dpp v176, v36, v164 row_ror:15 row_mask:0xf bank_mask:0xf
	v_fmac_f32_dpp v177, v37, v165 row_ror:15 row_mask:0xf bank_mask:0xf
	s_mov_b64 exec, s[42:43]
	global_store_dwordx4 v202, v[74:77], s[30:31]
	s_bitcmp1_b32 s27, 0
	s_cbranch_scc0 .Lmy_f1_t10
	s_add_u32 s0, s30, 0x2c00
	s_addc_u32 s1, s31, 0
	global_store_dwordx4 v202, v[166:169], s[0:1]
	s_add_u32 s0, s0, 0x2c00
	s_addc_u32 s1, s1, 0
	global_store_dwordx4 v202, v[58:61], s[0:1]

; __device__ __forceinline__ unsigned cvt_pk_bf16(float lo, float hi) { unsigned r; asm volatile("v_cvt_pk_bf16_f32 %0, %1, %2" : "=v"(r) : "v"(lo), "v"(hi)); return r; }
; __device__ __forceinline__ float silu_f(float a) { return a * __builtin_amdgcn_rcpf(1.0f + __expf(-a)); }
;     __device__ __forceinline__ void operator()(const f32x4 (&acc)[2][2][4][2], const pg8::Unit& u, int wr, int wc, int fr, int fq) const {
;     ...
;                         u32x2 w; w.x = cvt_pk_bf16(silu_f(pre[m][0]) * vv[0], silu_f(pre[m][1]) * vv[1]); w.y = cvt_pk_bf16(silu_f(pre[m][2]) * vv[2], silu_f(pre[m][3]) * vv[3]);
;                         if (n == 0) uw0[m] = w;
;                         else if (!need_fix) { const int row = rowt + lane_r + ai * 128 + m * 16; *(u32x4*)(U + (size_t)row * DFF + fb) = (u32x4){uw0[m].x, uw0[m].y, w.x, w.y}; }
.Lmy_f1_u10:
	s_cmp_lg_u64 s[38:39], 0
	s_cbranch_scc0 .Lmy_f1_ns4
	global_store_dwordx4 v204, v[58:61], s[0:1] sc1
	s_branch .Lmy_f1_ds4

; __device__ __forceinline__ unsigned cvt_pk_bf16(float lo, float hi) { unsigned r; asm volatile("v_cvt_pk_bf16_f32 %0, %1, %2" : "=v"(r) : "v"(lo), "v"(hi)); return r; }
; __device__ __forceinline__ float silu_f(float a) { return a * __builtin_amdgcn_rcpf(1.0f + __expf(-a)); }
;     __device__ __forceinline__ void operator()(const f32x4 (&acc)[2][2][4][2], const pg8::Unit& u, int wr, int wc, int fr, int fq) const {
;     ...
;                     for (int m = 0; m < 4; ++m) {
;                         const bool top = (m == 0 && fr == 0), bot = (m == 3 && fr == 15);
;                         const bool need_fix = (top && !seq_first) || (bot && !seq_last);
;                         const f32x4 vv = acc[ai][1][m][n];
;                         if (top || bot) {
;                             float* e = EDGE + ((size_t)(chunk * 2 + (bot ? 1 : 0)) * 3) * DFF + f0;
;                             *(f32x4*)e = acc[ai][0][m][n];
;                             if (need_fix) { *(f32x4*)(e + DFF) = pre[m]; *(f32x4*)(e + 2 * DFF) = vv; }
;                         }
;                         u32x2 w; w.x = cvt_pk_bf16(silu_f(pre[m][0]) * vv[0], silu_f(pre[m][1]) * vv[1]); w.y = cvt_pk_bf16(silu_f(pre[m][2]) * vv[2], silu_f(pre[m][3]) * vv[3]);
;                         if (n == 0) uw0[m] = w;
;                         else if (!need_fix) { const int row = rowt + lane_r + ai * 128 + m * 16; *(u32x4*)(U + (size_t)row * DFF + fb) = (u32x4){uw0[m].x, uw0[m].y, w.x, w.y}; }
.Lmy_f1_ds4:
	s_mov_b64 exec, s[56:57]
	s_add_u32 s0, s44, 0xc6000
	s_addc_u32 s1, s45, 0
	s_cmp_lg_u64 s[38:39], 0
	s_cbranch_scc0 .Lmy_f1_ns5
	global_store_dwordx4 v204, v[42:45], s[0:1] sc1
	s_branch .Lmy_f1_ds5
.Lmy_f1_ns5:
	global_store_dwordx4 v204, v[42:45], s[0:1]
.Lmy_f1_ds5:
	s_add_u32 s0, s44, 0xdc000
	s_addc_u32 s1, s45, 0
	s_cmp_lg_u64 s[38:39], 0
	s_cbranch_scc0 .Lmy_f1_ns6
	global_store_dwordx4 v204, v[26:29], s[0:1] sc1
	s_branch .Lmy_f1_ds6
.Lmy_f1_ns6:
	global_store_dwordx4 v204, v[26:29], s[0:1]
.Lmy_f1_ds6:
	s_add_u32 s0, s44, 0xf2000
	s_addc_u32 s1, s45, 0
	s_bitcmp1_b32 s27, 1
	s_cbranch_scc0 .Lmy_f1_u13
	s_andn2_b64 exec, s[56:57], s[40:41]
.Lmy_f1_u13:
	s_cmp_lg_u64 s[38:39], 0
	s_cbranch_scc0 .Lmy_f1_ns7
	global_store_dwordx4 v204, v[18:21], s[0:1] sc1
	s_branch .Lmy_f1_ds7

;     __device__ __forceinline__ void operator()(const f32x4 (&acc)[2][2][4][2], const pg8::Unit& u, int wr, int wc, int fr, int fq) const {
;     ...
;                         else if (!need_fix) { const int row = rowt + lane_r + ai * 128 + m * 16; *(u32x4*)(U + (size_t)row * DFF + fb) = (u32x4){uw0[m].x, uw0[m].y, w.x, w.y}; }
;                     }
;                 }
;             }
.Lmy_f1_ds7:
	s_mov_b64 exec, s[56:57]
	v_readlane_b32 s56, v249, 0
	v_readlane_b32 s57, v249, 1
	s_nop 1
	s_branch .LBB0_848
